# phase 3: the 128 swa_sample items moved from second-dispatched work-groups (which finished last, ~129 us) to 64 lightly loaded first-dispatched ones
# speedup vs baseline: 1.0117x; 1.0058x over previous
.LBB0_367:
	v_writelane_b32 v250, s77, 24
	v_writelane_b32 v250, s76, 26
	s_nop 0
	s_sub_i32 s0, s92, 0x90
	s_cmp_lt_u32 s0, 16
	s_cbranch_scc1 .Lss_ok
	s_sub_i32 s0, s92, 0x98
	s_sub_i32 s1, s0, 16
	s_cmp_lt_u32 s1, 48
	s_cbranch_scc1 .Lss_ok
	s_movk_i32 s0, 0x80
.Lss_ok:
	v_writelane_b32 v250, s0, 21
	s_cmpk_gt_i32 s0, 0x7f
	s_cbranch_scc1 .LBB0_453
	v_readlane_b32 s0, v252, 13
	v_readlane_b32 s14, v252, 27
	v_readlane_b32 s15, v252, 28
	s_add_u32 s0, s14, 0x4249000
	s_addc_u32 s90, s15, 0
	s_add_u32 s33, s14, 0x4a49000
	v_writelane_b32 v250, s0, 28
	s_addc_u32 s0, s15, 0
	v_readlane_b32 s1, v252, 14
	v_readlane_b32 s2, v252, 15
	v_readlane_b32 s3, v252, 16
	v_writelane_b32 v250, s0, 30
	v_readlane_b32 s2, v252, 2
	v_readlane_b32 s0, v250, 21
	s_add_i32 s93, s0, 0x4020
	s_movk_i32 s94, 0xff
	s_movk_i32 s95, 0x204
	v_mov_b32_e32 v61, 0
	v_mov_b32_e32 v128, 0x11200
	v_mov_b32_e32 v129, 0x10200
	v_mbcnt_hi_u32_b32 v130, -1, v219
	v_mov_b32_e32 v131, 1
	s_mov_b32 s16, s0
	v_readlane_b32 s4, v252, 17
	v_readlane_b32 s5, v252, 18
	v_readlane_b32 s6, v252, 19
	v_readlane_b32 s7, v252, 20
	v_readlane_b32 s8, v252, 21
	v_readlane_b32 s9, v252, 22
	v_readlane_b32 s10, v252, 23
	v_readlane_b32 s11, v252, 24
	v_readlane_b32 s12, v252, 25
	v_readlane_b32 s13, v252, 26
	v_readlane_b32 s1, v250, 10
	v_readlane_b32 s3, v252, 3

.LBB0_435:
	v_add_u32_e32 v5, 0x10200, v3
	ds_read_b128 v[6:9], v5
	ds_read2_b64 v[10:13], v4 offset1:129
	v_add_u32_e32 v5, 0x60c, v4
	s_add_i32 s0, s0, -16
	s_cmp_lg_u32 s0, 0
	s_waitcnt lgkmcnt(0)
	v_pk_fma_f32 v[0:1], v[6:7], v[10:11], v[0:1] op_sel_hi:[0,1,1]
	ds_read2_b32 v[10:11], v4 offset0:129 offset1:130
	s_waitcnt lgkmcnt(0)
	v_pk_fma_f32 v[0:1], v[6:7], v[10:11], v[0:1] op_sel:[1,0,0]
	ds_read2_b32 v[6:7], v5 offset1:1
	v_pk_fma_f32 v[0:1], v[8:9], v[12:13], v[0:1] op_sel_hi:[0,1,1]
	v_mov_b32_e32 v8, v9
	v_add_u32_e32 v5, 0x10210, v3
	s_waitcnt lgkmcnt(0)
	v_pk_fma_f32 v[0:1], v[8:9], v[6:7], v[0:1] op_sel_hi:[0,1,1]
	ds_read_b128 v[6:9], v5
	v_add_u32_e32 v5, 0x800, v4
	ds_read2_b64 v[10:13], v5 offset0:2 offset1:131
	v_add_u32_e32 v5, 0xa14, v4
	s_waitcnt lgkmcnt(0)
	v_pk_fma_f32 v[0:1], v[6:7], v[10:11], v[0:1] op_sel_hi:[0,1,1]
	ds_read2_b32 v[10:11], v5 offset1:1
	v_add_u32_e32 v5, 0xe1c, v4
	s_waitcnt lgkmcnt(0)
	v_pk_fma_f32 v[0:1], v[6:7], v[10:11], v[0:1] op_sel:[1,0,0]
	ds_read2_b32 v[6:7], v5 offset1:1
	v_pk_fma_f32 v[0:1], v[8:9], v[12:13], v[0:1] op_sel_hi:[0,1,1]
	v_mov_b32_e32 v8, v9
	v_add_u32_e32 v5, 0x10220, v3
	s_waitcnt lgkmcnt(0)
	v_pk_fma_f32 v[0:1], v[8:9], v[6:7], v[0:1] op_sel_hi:[0,1,1]
	ds_read_b128 v[6:9], v5
	v_add_u32_e32 v5, 0x1000, v4
	ds_read2_b64 v[10:13], v5 offset0:4 offset1:133
	v_add_u32_e32 v5, 0x1224, v4
	s_waitcnt lgkmcnt(0)
	v_pk_fma_f32 v[0:1], v[6:7], v[10:11], v[0:1] op_sel_hi:[0,1,1]
	ds_read2_b32 v[10:11], v5 offset1:1
	v_add_u32_e32 v5, 0x162c, v4
	s_waitcnt lgkmcnt(0)
	v_pk_fma_f32 v[0:1], v[6:7], v[10:11], v[0:1] op_sel:[1,0,0]
	ds_read2_b32 v[6:7], v5 offset1:1
	v_pk_fma_f32 v[0:1], v[8:9], v[12:13], v[0:1] op_sel_hi:[0,1,1]
	v_mov_b32_e32 v8, v9
	v_add_u32_e32 v5, 0x10230, v3
	v_add_u32_e32 v3, 64, v3
	s_waitcnt lgkmcnt(0)
	v_pk_fma_f32 v[0:1], v[8:9], v[6:7], v[0:1] op_sel_hi:[0,1,1]
	ds_read_b128 v[6:9], v5
	v_add_u32_e32 v5, 0x1800, v4
	ds_read2_b64 v[10:13], v5 offset0:6 offset1:135
	v_add_u32_e32 v5, 0x1a34, v4
	s_waitcnt lgkmcnt(0)
	v_pk_fma_f32 v[0:1], v[6:7], v[10:11], v[0:1] op_sel_hi:[0,1,1]
	ds_read2_b32 v[10:11], v5 offset1:1
	v_add_u32_e32 v5, 0x1e3c, v4
	v_add_u32_e32 v4, 0x2040, v4
	s_waitcnt lgkmcnt(0)
	v_pk_fma_f32 v[0:1], v[6:7], v[10:11], v[0:1] op_sel:[1,0,0]
	ds_read2_b32 v[6:7], v5 offset1:1
	v_pk_fma_f32 v[0:1], v[8:9], v[12:13], v[0:1] op_sel_hi:[0,1,1]
	v_mov_b32_e32 v8, v9
	s_waitcnt lgkmcnt(0)
	v_pk_fma_f32 v[0:1], v[8:9], v[6:7], v[0:1] op_sel_hi:[0,1,1]
	s_cbranch_scc1 .LBB0_435
	v_and_b32_e32 v6, 62, v2
	v_lshlrev_b32_e32 v2, 6, v132
	v_ashrrev_i32_e32 v3, 31, v2
	v_or_b32_e32 v4, v2, v6
	v_mov_b32_e32 v5, v3
	v_lshl_add_u64 v[4:5], v[4:5], 1, s[40:41]
	global_load_dword v4, v[4:5], off offset:1536
	v_lshlrev_b32_e32 v60, 1, v6
	s_lshl_b64 s[0:1], s[18:19], 11
	v_readlane_b32 s2, v250, 17
	v_readlane_b32 s3, v250, 18
	s_add_u32 s0, s2, s0
	s_addc_u32 s1, s3, s1
	v_lshl_add_u64 v[2:3], v[2:3], 1, s[0:1]
	s_add_i32 s16, s16, 64
	s_add_i32 s93, s93, 64
	v_lshl_add_u64 v[2:3], v[2:3], 0, v[60:61]
	s_cmpk_gt_i32 s16, 0x7f
	s_waitcnt vmcnt(0)
	v_and_b32_e32 v6, 0xffff0000, v4
	v_lshlrev_b32_e32 v7, 16, v4
	v_mul_f32_e32 v4, 0xbfb8aa3b, v7
	v_mul_f32_e32 v5, 0xbfb8aa3b, v6
	v_exp_f32_e32 v4, v4
	v_exp_f32_e32 v5, v5
	s_nop 0
	v_pk_add_f32 v[4:5], v[4:5], 1.0 op_sel_hi:[1,0]
	s_nop 0
	v_div_scale_f32 v8, s[0:1], v5, v5, v6
	v_rcp_f32_e32 v9, v8
	s_nop 0
	v_fma_f32 v10, -v8, v9, 1.0
	v_fmac_f32_e32 v9, v10, v9
	v_div_scale_f32 v10, vcc, v6, v5, v6
	v_mul_f32_e32 v11, v10, v9
	v_fma_f32 v12, -v8, v11, v10
	v_fmac_f32_e32 v11, v12, v9
	v_fma_f32 v8, -v8, v11, v10
	v_div_fmas_f32 v8, v8, v9, v11
	v_div_fixup_f32 v5, v8, v5, v6
	v_div_scale_f32 v6, s[0:1], v4, v4, v7
	v_rcp_f32_e32 v8, v6
	s_movk_i32 s0, 0x7fff
	v_fma_f32 v9, -v6, v8, 1.0
	v_fmac_f32_e32 v8, v9, v8
	v_div_scale_f32 v9, vcc, v7, v4, v7
	v_mul_f32_e32 v10, v9, v8
	v_fma_f32 v11, -v6, v10, v9
	v_fmac_f32_e32 v10, v11, v8
	v_fma_f32 v6, -v6, v10, v9
	v_div_fmas_f32 v6, v6, v8, v10
	v_div_fixup_f32 v4, v6, v4, v7
	v_pk_mul_f32 v[0:1], v[0:1], v[4:5]
	s_nop 0
	v_and_b32_sdwa v4, v1, v131 dst_sel:DWORD dst_unused:UNUSED_PAD src0_sel:WORD_1 src1_sel:DWORD
	v_and_b32_sdwa v5, v0, v131 dst_sel:DWORD dst_unused:UNUSED_PAD src0_sel:WORD_1 src1_sel:DWORD
	v_add3_u32 v0, v0, v5, s0
	v_add3_u32 v1, v1, v4, s0
	s_mov_b32 s0, 0x7060302
	v_perm_b32 v0, v1, v0, s0
	global_store_dword v[2:3], v0, off
	s_barrier
	s_cbranch_scc0 .LBB0_369
	s_branch .LBB0_453
